# DSA P.V loop tail: vmcnt(0) before the operand copies replaced by a counted vmcnt(7..0) ladder in load order
# speedup vs baseline: 1.0013x; 1.0013x over previous
.LBB0_275:
	v_min_i32_e32 v240, s50, v103
	v_lshl_add_u32 v240, v240, 5, v202
	ds_read_b128 v[208:211], v240
	v_add_u32_e32 v241, 4, v103
	v_min_i32_e32 v241, s50, v241
	v_lshl_add_u32 v241, v241, 5, v202
	ds_read_b128 v[212:215], v241
	v_add_u32_e32 v242, 8, v103
	v_min_i32_e32 v242, s50, v242
	v_lshl_add_u32 v242, v242, 5, v202
	ds_read_b128 v[216:219], v242
	v_add_u32_e32 v243, 12, v103
	v_min_i32_e32 v243, s50, v243
	v_lshl_add_u32 v243, v243, 5, v202
	ds_read_b128 v[220:223], v243
	v_add_u32_e32 v244, 16, v103
	v_min_i32_e32 v244, s50, v244
	v_lshl_add_u32 v244, v244, 5, v202
	ds_read_b128 v[224:227], v244
	v_add_u32_e32 v245, 20, v103
	v_min_i32_e32 v245, s50, v245
	v_lshl_add_u32 v245, v245, 5, v202
	ds_read_b128 v[228:231], v245
	v_add_u32_e32 v246, 24, v103
	v_min_i32_e32 v246, s50, v246
	v_lshl_add_u32 v246, v246, 5, v202
	ds_read_b128 v[232:235], v246
	v_add_u32_e32 v247, 28, v103
	v_min_i32_e32 v247, s50, v247
	v_lshl_add_u32 v247, v247, 5, v202
	ds_read_b128 v[236:239], v247
	v_cmp_lt_u32_e32 vcc, s50, v103
	v_lshlrev_b32_e32 v114, 16, v62
	v_and_b32_e32 v115, 0xffff0000, v62
	v_lshlrev_b32_e32 v62, 16, v63
	s_waitcnt lgkmcnt(7)
	v_cndmask_b32_e64 v110, v211, 0, vcc
	v_cndmask_b32_e64 v108, v210, 0, vcc
	v_cndmask_b32_e64 v112, v209, 0, vcc
	v_cndmask_b32_e64 v106, v208, 0, vcc
	v_and_b32_e32 v63, 0xffff0000, v63
	v_pk_fma_f32 v[88:89], v[106:107], v[62:63], v[88:89] op_sel_hi:[0,1,1]
	v_pk_fma_f32 v[86:87], v[112:113], v[62:63], v[86:87] op_sel_hi:[0,1,1]
	v_pk_fma_f32 v[84:85], v[108:109], v[62:63], v[84:85] op_sel_hi:[0,1,1]
	v_pk_fma_f32 v[82:83], v[110:111], v[62:63], v[82:83] op_sel_hi:[0,1,1]
	v_add_u32_e32 v62, 4, v103
	v_cmp_lt_u32_e32 vcc, s50, v62
	v_lshlrev_b32_e32 v116, 16, v64
	v_and_b32_e32 v117, 0xffff0000, v64
	v_lshlrev_b32_e32 v64, 16, v65
	v_and_b32_e32 v65, 0xffff0000, v65
	v_pk_fma_f32 v[72:73], v[106:107], v[64:65], v[72:73] op_sel_hi:[0,1,1]
	v_pk_fma_f32 v[70:71], v[112:113], v[64:65], v[70:71] op_sel_hi:[0,1,1]
	v_pk_fma_f32 v[68:69], v[108:109], v[64:65], v[68:69] op_sel_hi:[0,1,1]
	v_pk_fma_f32 v[66:67], v[110:111], v[64:65], v[66:67] op_sel_hi:[0,1,1]
	v_pk_fma_f32 v[92:93], v[106:107], v[114:115], v[92:93] op_sel_hi:[0,1,1]
	v_pk_fma_f32 v[80:81], v[106:107], v[116:117], v[80:81] op_sel_hi:[0,1,1]
	v_pk_fma_f32 v[94:95], v[108:109], v[114:115], v[94:95] op_sel_hi:[0,1,1]
	v_pk_fma_f32 v[74:75], v[108:109], v[116:117], v[74:75] op_sel_hi:[0,1,1]
	v_pk_fma_f32 v[90:91], v[110:111], v[114:115], v[90:91] op_sel_hi:[0,1,1]
	v_pk_fma_f32 v[76:77], v[110:111], v[116:117], v[76:77] op_sel_hi:[0,1,1]
	s_waitcnt lgkmcnt(6)
	v_cndmask_b32_e64 v106, v215, 0, vcc
	v_cndmask_b32_e64 v64, v214, 0, vcc
	v_cndmask_b32_e64 v108, v213, 0, vcc
	v_cndmask_b32_e64 v62, v212, 0, vcc
	v_lshlrev_b32_e32 v110, 16, v58
	v_and_b32_e32 v111, 0xffff0000, v58
	v_lshlrev_b32_e32 v58, 16, v59
	v_and_b32_e32 v59, 0xffff0000, v59
	v_pk_fma_f32 v[88:89], v[62:63], v[58:59], v[88:89] op_sel_hi:[0,1,1]
	v_pk_fma_f32 v[86:87], v[108:109], v[58:59], v[86:87] op_sel_hi:[0,1,1]
	v_pk_fma_f32 v[84:85], v[64:65], v[58:59], v[84:85] op_sel_hi:[0,1,1]
	v_pk_fma_f32 v[82:83], v[106:107], v[58:59], v[82:83] op_sel_hi:[0,1,1]
	v_add_u32_e32 v58, 8, v103
	v_cmp_lt_u32_e32 vcc, s50, v58
	v_pk_fma_f32 v[96:97], v[112:113], v[114:115], v[96:97] op_sel_hi:[0,1,1]
	v_pk_fma_f32 v[78:79], v[112:113], v[116:117], v[78:79] op_sel_hi:[0,1,1]
	v_lshlrev_b32_e32 v112, 16, v60
	v_and_b32_e32 v113, 0xffff0000, v60
	v_lshlrev_b32_e32 v60, 16, v61
	v_and_b32_e32 v61, 0xffff0000, v61
	v_pk_fma_f32 v[72:73], v[62:63], v[60:61], v[72:73] op_sel_hi:[0,1,1]
	v_pk_fma_f32 v[70:71], v[108:109], v[60:61], v[70:71] op_sel_hi:[0,1,1]
	v_pk_fma_f32 v[68:69], v[64:65], v[60:61], v[68:69] op_sel_hi:[0,1,1]
	v_pk_fma_f32 v[66:67], v[106:107], v[60:61], v[66:67] op_sel_hi:[0,1,1]
	v_pk_fma_f32 v[80:81], v[62:63], v[112:113], v[80:81] op_sel_hi:[0,1,1]
	v_pk_fma_f32 v[62:63], v[62:63], v[110:111], v[92:93] op_sel_hi:[0,1,1]
	v_pk_fma_f32 v[92:93], v[108:109], v[110:111], v[96:97] op_sel_hi:[0,1,1]
	v_pk_fma_f32 v[74:75], v[64:65], v[112:113], v[74:75] op_sel_hi:[0,1,1]
	v_pk_fma_f32 v[64:65], v[64:65], v[110:111], v[94:95] op_sel_hi:[0,1,1]
	v_pk_fma_f32 v[76:77], v[106:107], v[112:113], v[76:77] op_sel_hi:[0,1,1]
	v_pk_fma_f32 v[90:91], v[106:107], v[110:111], v[90:91] op_sel_hi:[0,1,1]
	s_waitcnt lgkmcnt(5)
	v_cndmask_b32_e64 v94, v219, 0, vcc
	v_cndmask_b32_e64 v60, v218, 0, vcc
	v_cndmask_b32_e64 v96, v217, 0, vcc
	v_cndmask_b32_e64 v58, v216, 0, vcc
	v_lshlrev_b32_e32 v106, 16, v54
	v_and_b32_e32 v107, 0xffff0000, v54
	v_lshlrev_b32_e32 v54, 16, v55
	v_and_b32_e32 v55, 0xffff0000, v55
	v_pk_fma_f32 v[88:89], v[58:59], v[54:55], v[88:89] op_sel_hi:[0,1,1]
	v_pk_fma_f32 v[86:87], v[96:97], v[54:55], v[86:87] op_sel_hi:[0,1,1]
	v_pk_fma_f32 v[84:85], v[60:61], v[54:55], v[84:85] op_sel_hi:[0,1,1]
	v_pk_fma_f32 v[82:83], v[94:95], v[54:55], v[82:83] op_sel_hi:[0,1,1]
	v_add_u32_e32 v54, 12, v103
	v_cmp_lt_u32_e32 vcc, s50, v54
	v_pk_fma_f32 v[78:79], v[108:109], v[112:113], v[78:79] op_sel_hi:[0,1,1]
	v_lshlrev_b32_e32 v108, 16, v56
	v_and_b32_e32 v109, 0xffff0000, v56
	v_lshlrev_b32_e32 v56, 16, v57
	v_and_b32_e32 v57, 0xffff0000, v57
	v_pk_fma_f32 v[62:63], v[58:59], v[106:107], v[62:63] op_sel_hi:[0,1,1]
	v_pk_fma_f32 v[80:81], v[58:59], v[108:109], v[80:81] op_sel_hi:[0,1,1]
	v_pk_fma_f32 v[58:59], v[58:59], v[56:57], v[72:73] op_sel_hi:[0,1,1]
	v_pk_fma_f32 v[70:71], v[96:97], v[56:57], v[70:71] op_sel_hi:[0,1,1]
	v_pk_fma_f32 v[64:65], v[60:61], v[106:107], v[64:65] op_sel_hi:[0,1,1]
	v_pk_fma_f32 v[74:75], v[60:61], v[108:109], v[74:75] op_sel_hi:[0,1,1]
	v_pk_fma_f32 v[60:61], v[60:61], v[56:57], v[68:69] op_sel_hi:[0,1,1]
	v_pk_fma_f32 v[66:67], v[94:95], v[56:57], v[66:67] op_sel_hi:[0,1,1]
	v_pk_fma_f32 v[72:73], v[96:97], v[106:107], v[92:93] op_sel_hi:[0,1,1]
	v_pk_fma_f32 v[78:79], v[96:97], v[108:109], v[78:79] op_sel_hi:[0,1,1]
	v_pk_fma_f32 v[68:69], v[94:95], v[106:107], v[90:91] op_sel_hi:[0,1,1]
	v_pk_fma_f32 v[76:77], v[94:95], v[108:109], v[76:77] op_sel_hi:[0,1,1]
	s_waitcnt lgkmcnt(4)
	v_cndmask_b32_e64 v90, v223, 0, vcc
	v_cndmask_b32_e64 v56, v222, 0, vcc
	v_cndmask_b32_e64 v92, v221, 0, vcc
	v_cndmask_b32_e64 v54, v220, 0, vcc
	v_lshlrev_b32_e32 v94, 16, v50
	v_and_b32_e32 v95, 0xffff0000, v50
	v_lshlrev_b32_e32 v50, 16, v51
	v_and_b32_e32 v51, 0xffff0000, v51
	v_lshlrev_b32_e32 v96, 16, v52
	v_and_b32_e32 v97, 0xffff0000, v52
	v_lshlrev_b32_e32 v52, 16, v53
	v_and_b32_e32 v53, 0xffff0000, v53
	v_pk_fma_f32 v[58:59], v[54:55], v[52:53], v[58:59] op_sel_hi:[0,1,1]
	v_pk_fma_f32 v[80:81], v[54:55], v[96:97], v[80:81] op_sel_hi:[0,1,1]
	v_pk_fma_f32 v[88:89], v[54:55], v[50:51], v[88:89] op_sel_hi:[0,1,1]
	v_pk_fma_f32 v[54:55], v[54:55], v[94:95], v[62:63] op_sel_hi:[0,1,1]
	v_pk_fma_f32 v[62:63], v[92:93], v[52:53], v[70:71] op_sel_hi:[0,1,1]
	v_pk_fma_f32 v[70:71], v[92:93], v[96:97], v[78:79] op_sel_hi:[0,1,1]
	v_pk_fma_f32 v[78:79], v[92:93], v[50:51], v[86:87] op_sel_hi:[0,1,1]
	v_pk_fma_f32 v[60:61], v[56:57], v[52:53], v[60:61] op_sel_hi:[0,1,1]
	v_pk_fma_f32 v[74:75], v[56:57], v[96:97], v[74:75] op_sel_hi:[0,1,1]
	v_pk_fma_f32 v[84:85], v[56:57], v[50:51], v[84:85] op_sel_hi:[0,1,1]
	v_pk_fma_f32 v[56:57], v[56:57], v[94:95], v[64:65] op_sel_hi:[0,1,1]
	v_pk_fma_f32 v[64:65], v[90:91], v[52:53], v[66:67] op_sel_hi:[0,1,1]
	v_pk_fma_f32 v[66:67], v[90:91], v[96:97], v[76:77] op_sel_hi:[0,1,1]
	v_pk_fma_f32 v[76:77], v[90:91], v[50:51], v[82:83] op_sel_hi:[0,1,1]
	v_add_u32_e32 v50, 16, v103
	v_cmp_lt_u32_e32 vcc, s50, v50
	v_pk_fma_f32 v[72:73], v[92:93], v[94:95], v[72:73] op_sel_hi:[0,1,1]
	v_pk_fma_f32 v[68:69], v[90:91], v[94:95], v[68:69] op_sel_hi:[0,1,1]
	v_lshlrev_b32_e32 v90, 16, v46
	v_and_b32_e32 v91, 0xffff0000, v46
	s_waitcnt lgkmcnt(3)
	v_cndmask_b32_e64 v82, v227, 0, vcc
	v_cndmask_b32_e64 v52, v226, 0, vcc
	v_cndmask_b32_e64 v86, v225, 0, vcc
	v_cndmask_b32_e64 v50, v224, 0, vcc
	v_lshlrev_b32_e32 v46, 16, v47
	v_and_b32_e32 v47, 0xffff0000, v47
	v_lshlrev_b32_e32 v92, 16, v48
	v_and_b32_e32 v93, 0xffff0000, v48
	v_lshlrev_b32_e32 v48, 16, v49
	v_and_b32_e32 v49, 0xffff0000, v49
	v_pk_fma_f32 v[54:55], v[50:51], v[90:91], v[54:55] op_sel_hi:[0,1,1]
	v_pk_fma_f32 v[88:89], v[50:51], v[46:47], v[88:89] op_sel_hi:[0,1,1]
	v_pk_fma_f32 v[80:81], v[50:51], v[92:93], v[80:81] op_sel_hi:[0,1,1]
	v_pk_fma_f32 v[50:51], v[50:51], v[48:49], v[58:59] op_sel_hi:[0,1,1]
	v_pk_fma_f32 v[58:59], v[86:87], v[90:91], v[72:73] op_sel_hi:[0,1,1]
	v_pk_fma_f32 v[72:73], v[86:87], v[46:47], v[78:79] op_sel_hi:[0,1,1]
	v_pk_fma_f32 v[56:57], v[52:53], v[90:91], v[56:57] op_sel_hi:[0,1,1]
	v_pk_fma_f32 v[78:79], v[52:53], v[46:47], v[84:85] op_sel_hi:[0,1,1]
	v_pk_fma_f32 v[74:75], v[52:53], v[92:93], v[74:75] op_sel_hi:[0,1,1]
	v_pk_fma_f32 v[52:53], v[52:53], v[48:49], v[60:61] op_sel_hi:[0,1,1]
	v_pk_fma_f32 v[60:61], v[82:83], v[90:91], v[68:69] op_sel_hi:[0,1,1]
	v_pk_fma_f32 v[68:69], v[82:83], v[46:47], v[76:77] op_sel_hi:[0,1,1]
	v_add_u32_e32 v46, 20, v103
	v_cmp_lt_u32_e32 vcc, s50, v46
	v_pk_fma_f32 v[62:63], v[86:87], v[48:49], v[62:63] op_sel_hi:[0,1,1]
	v_pk_fma_f32 v[64:65], v[82:83], v[48:49], v[64:65] op_sel_hi:[0,1,1]
	v_pk_fma_f32 v[70:71], v[86:87], v[92:93], v[70:71] op_sel_hi:[0,1,1]
	v_pk_fma_f32 v[66:67], v[82:83], v[92:93], v[66:67] op_sel_hi:[0,1,1]
	v_lshlrev_b32_e32 v84, 16, v10
	v_and_b32_e32 v85, 0xffff0000, v10
	s_waitcnt lgkmcnt(2)
	v_cndmask_b32_e64 v76, v231, 0, vcc
	v_cndmask_b32_e64 v48, v230, 0, vcc
	v_cndmask_b32_e64 v82, v229, 0, vcc
	v_cndmask_b32_e64 v46, v228, 0, vcc
	v_lshlrev_b32_e32 v10, 16, v11
	v_and_b32_e32 v11, 0xffff0000, v11
	v_lshlrev_b32_e32 v86, 16, v12
	v_and_b32_e32 v87, 0xffff0000, v12
	v_lshlrev_b32_e32 v12, 16, v13
	v_and_b32_e32 v13, 0xffff0000, v13
	v_pk_fma_f32 v[50:51], v[46:47], v[12:13], v[50:51] op_sel_hi:[0,1,1]
	v_pk_fma_f32 v[80:81], v[46:47], v[86:87], v[80:81] op_sel_hi:[0,1,1]
	v_pk_fma_f32 v[88:89], v[46:47], v[10:11], v[88:89] op_sel_hi:[0,1,1]
	v_pk_fma_f32 v[46:47], v[46:47], v[84:85], v[54:55] op_sel_hi:[0,1,1]
	v_pk_fma_f32 v[54:55], v[82:83], v[12:13], v[62:63] op_sel_hi:[0,1,1]
	v_pk_fma_f32 v[62:63], v[82:83], v[86:87], v[70:71] op_sel_hi:[0,1,1]
	v_pk_fma_f32 v[70:71], v[82:83], v[10:11], v[72:73] op_sel_hi:[0,1,1]
	v_pk_fma_f32 v[52:53], v[48:49], v[12:13], v[52:53] op_sel_hi:[0,1,1]
	v_pk_fma_f32 v[72:73], v[48:49], v[86:87], v[74:75] op_sel_hi:[0,1,1]
	v_pk_fma_f32 v[74:75], v[48:49], v[10:11], v[78:79] op_sel_hi:[0,1,1]
	v_pk_fma_f32 v[48:49], v[48:49], v[84:85], v[56:57] op_sel_hi:[0,1,1]
	v_pk_fma_f32 v[56:57], v[76:77], v[12:13], v[64:65] op_sel_hi:[0,1,1]
	v_pk_fma_f32 v[64:65], v[76:77], v[86:87], v[66:67] op_sel_hi:[0,1,1]
	v_pk_fma_f32 v[66:67], v[76:77], v[10:11], v[68:69] op_sel_hi:[0,1,1]
	v_add_u32_e32 v10, 24, v103
	v_cmp_lt_u32_e32 vcc, s50, v10
	v_pk_fma_f32 v[58:59], v[82:83], v[84:85], v[58:59] op_sel_hi:[0,1,1]
	v_pk_fma_f32 v[60:61], v[76:77], v[84:85], v[60:61] op_sel_hi:[0,1,1]
	v_lshlrev_b32_e32 v78, 16, v6
	v_and_b32_e32 v79, 0xffff0000, v6
	s_waitcnt lgkmcnt(1)
	v_cndmask_b32_e64 v68, v235, 0, vcc
	v_cndmask_b32_e64 v12, v234, 0, vcc
	v_cndmask_b32_e64 v76, v233, 0, vcc
	v_cndmask_b32_e64 v10, v232, 0, vcc
	v_lshlrev_b32_e32 v6, 16, v7
	v_and_b32_e32 v7, 0xffff0000, v7
	v_lshlrev_b32_e32 v82, 16, v8
	v_and_b32_e32 v83, 0xffff0000, v8
	v_lshlrev_b32_e32 v8, 16, v9
	v_and_b32_e32 v9, 0xffff0000, v9
	v_pk_fma_f32 v[46:47], v[10:11], v[78:79], v[46:47] op_sel_hi:[0,1,1]
	v_pk_fma_f32 v[84:85], v[10:11], v[6:7], v[88:89] op_sel_hi:[0,1,1]
	v_pk_fma_f32 v[80:81], v[10:11], v[82:83], v[80:81] op_sel_hi:[0,1,1]
	v_pk_fma_f32 v[10:11], v[10:11], v[8:9], v[50:51] op_sel_hi:[0,1,1]
	v_pk_fma_f32 v[50:51], v[76:77], v[78:79], v[58:59] op_sel_hi:[0,1,1]
	v_pk_fma_f32 v[58:59], v[76:77], v[6:7], v[70:71] op_sel_hi:[0,1,1]
	v_pk_fma_f32 v[62:63], v[76:77], v[82:83], v[62:63] op_sel_hi:[0,1,1]
	v_pk_fma_f32 v[54:55], v[76:77], v[8:9], v[54:55] op_sel_hi:[0,1,1]
	v_pk_fma_f32 v[48:49], v[12:13], v[78:79], v[48:49] op_sel_hi:[0,1,1]
	v_pk_fma_f32 v[76:77], v[12:13], v[6:7], v[74:75] op_sel_hi:[0,1,1]
	v_pk_fma_f32 v[74:75], v[12:13], v[82:83], v[72:73] op_sel_hi:[0,1,1]
	v_pk_fma_f32 v[12:13], v[12:13], v[8:9], v[52:53] op_sel_hi:[0,1,1]
	v_pk_fma_f32 v[52:53], v[68:69], v[78:79], v[60:61] op_sel_hi:[0,1,1]
	v_pk_fma_f32 v[60:61], v[68:69], v[6:7], v[66:67] op_sel_hi:[0,1,1]
	v_add_u32_e32 v6, 28, v103
	v_cmp_lt_u32_e32 vcc, s50, v6
	v_pk_fma_f32 v[56:57], v[68:69], v[8:9], v[56:57] op_sel_hi:[0,1,1]
	v_pk_fma_f32 v[64:65], v[68:69], v[82:83], v[64:65] op_sel_hi:[0,1,1]
	v_lshlrev_b32_e32 v106, 16, v2
	v_and_b32_e32 v107, 0xffff0000, v2
	v_lshlrev_b32_e32 v2, 16, v3
	s_waitcnt lgkmcnt(0)
	v_cndmask_b32_e64 v90, v239, 0, vcc
	v_cndmask_b32_e64 v8, v238, 0, vcc
	v_cndmask_b32_e64 v66, v237, 0, vcc
	v_cndmask_b32_e64 v6, v236, 0, vcc
	v_and_b32_e32 v3, 0xffff0000, v3
	v_lshlrev_b32_e32 v82, 16, v4
	v_and_b32_e32 v83, 0xffff0000, v4
	v_lshlrev_b32_e32 v4, 16, v5
	v_and_b32_e32 v5, 0xffff0000, v5
	v_pk_fma_f32 v[72:73], v[6:7], v[4:5], v[10:11] op_sel_hi:[0,1,1]
	v_pk_fma_f32 v[80:81], v[6:7], v[82:83], v[80:81] op_sel_hi:[0,1,1]
	v_pk_fma_f32 v[88:89], v[6:7], v[2:3], v[84:85] op_sel_hi:[0,1,1]
	v_pk_fma_f32 v[92:93], v[6:7], v[106:107], v[46:47] op_sel_hi:[0,1,1]
	v_pk_fma_f32 v[70:71], v[66:67], v[4:5], v[54:55] op_sel_hi:[0,1,1]
	v_pk_fma_f32 v[78:79], v[66:67], v[82:83], v[62:63] op_sel_hi:[0,1,1]
	v_pk_fma_f32 v[86:87], v[66:67], v[2:3], v[58:59] op_sel_hi:[0,1,1]
	v_pk_fma_f32 v[96:97], v[66:67], v[106:107], v[50:51] op_sel_hi:[0,1,1]
	v_pk_fma_f32 v[68:69], v[8:9], v[4:5], v[12:13] op_sel_hi:[0,1,1]
	v_pk_fma_f32 v[74:75], v[8:9], v[82:83], v[74:75] op_sel_hi:[0,1,1]
	v_pk_fma_f32 v[84:85], v[8:9], v[2:3], v[76:77] op_sel_hi:[0,1,1]
	v_pk_fma_f32 v[94:95], v[8:9], v[106:107], v[48:49] op_sel_hi:[0,1,1]
	v_pk_fma_f32 v[66:67], v[90:91], v[4:5], v[56:57] op_sel_hi:[0,1,1]
	v_pk_fma_f32 v[76:77], v[90:91], v[82:83], v[64:65] op_sel_hi:[0,1,1]
	v_pk_fma_f32 v[82:83], v[90:91], v[2:3], v[60:61] op_sel_hi:[0,1,1]
	v_pk_fma_f32 v[90:91], v[90:91], v[106:107], v[52:53] op_sel_hi:[0,1,1]
	s_add_i32 s76, s76, 8
	s_andn2_b64 vcc, exec, s[34:35]
	v_mov_b32_e32 v103, v104
	s_waitcnt vmcnt(7)
	v_mov_b64_e32 v[62:63], v[14:15]
	v_mov_b64_e32 v[64:65], v[16:17]
	s_waitcnt vmcnt(6)
	v_mov_b64_e32 v[58:59], v[18:19]
	v_mov_b64_e32 v[60:61], v[20:21]
	s_waitcnt vmcnt(5)
	v_mov_b64_e32 v[54:55], v[22:23]
	v_mov_b64_e32 v[56:57], v[24:25]
	s_waitcnt vmcnt(4)
	v_mov_b64_e32 v[50:51], v[26:27]
	v_mov_b64_e32 v[52:53], v[28:29]
	s_waitcnt vmcnt(3)
	v_mov_b64_e32 v[46:47], v[30:31]
	v_mov_b64_e32 v[48:49], v[32:33]
	s_waitcnt vmcnt(2)
	v_mov_b64_e32 v[10:11], v[34:35]
	v_mov_b64_e32 v[12:13], v[36:37]
	s_waitcnt vmcnt(1)
	v_mov_b64_e32 v[6:7], v[38:39]
	v_mov_b64_e32 v[8:9], v[40:41]
	s_waitcnt vmcnt(0)
	v_mov_b64_e32 v[2:3], v[42:43]
	v_mov_b64_e32 v[4:5], v[44:45]
	s_cbranch_vccz .LBB0_241
